# speedup vs baseline: 1.0085x; 1.0039x over previous
; __device__ __forceinline__ u16 f2bf(float f) { return (u16)(pack2(f, 0.f) & 0xffffu); }
; __device__ __forceinline__ void attn_load_kv(PP p, int rb_l, int h, int P, int sb, int ks, int fr, int fq, bf16x8 (&kf)[2], bf16x4 (&vf)[4]) {
;     ...
;     const float* kp = p->ck + (((size_t)sb * PAST + ks + fr) * NH + h) * HD;
; #pragma unroll
;     for (int kk = 0; kk < 2; ++kk) {
;       float t8[8];
;       ld8f(kp + kk * 32 + fq * 8, t8);
; #pragma unroll
;       for (int i = 0; i < 8; ++i) kf[kk][i] = (short)f2bf(t8[i]);
;     }
; #pragma unroll
;     for (int mt = 0; mt < 4; ++mt)
; #pragma unroll
;       for (int i = 0; i < 4; ++i)
;         vf[mt][i] = (short)f2bf(p->cv[(((size_t)sb * PAST + ks + fq * 4 + i) * NH + h) * HD + mt * 16 + fr]);
.LBB0_515:
	s_andn2_saveexec_b64 s[20:21], s[8:9]
	s_cbranch_execz .LBB0_517
	s_load_dwordx4 s[8:11], s[0:1], 0x10
	v_mov_b32_e32 v193, v0
	s_waitcnt vmcnt(1)
	v_lshl_add_u64 v[188:189], s[14:15], 0, v[192:193]
	v_lshl_add_u64 v[102:103], v[188:189], 0, v[122:123]
	v_lshlrev_b64 v[102:103], 12, v[102:103]
	s_waitcnt lgkmcnt(0)
	v_lshl_add_u64 v[102:103], s[8:9], 0, v[102:103]
	v_lshl_add_u64 v[102:103], v[102:103], 0, v[160:161]
	v_mov_b32_e32 v149, v0
	s_waitcnt vmcnt(0)
	v_lshl_add_u64 v[190:191], v[102:103], 0, v[148:149]
	global_load_dwordx4 v[118:121], v[190:191], off offset:16
	global_load_dwordx4 v[102:105], v[190:191], off
	global_load_dwordx4 v[184:187], v[190:191], off offset:144
	global_load_dwordx4 v[238:241], v[190:191], off offset:128
	v_mov_b32_e32 v151, v0
	v_lshl_add_u64 v[242:243], v[188:189], 0, v[128:129]
	v_lshl_add_u64 v[244:245], s[10:11], 0, v[160:161]
	v_lshl_add_u64 v[244:245], v[244:245], 0, v[150:151]
	v_lshlrev_b64 v[242:243], 12, v[242:243]
	s_movk_i32 s8, 0x1000
	v_lshl_add_u64 v[190:191], v[244:245], 0, v[242:243]
	v_add_co_u32_e32 v192, vcc, s8, v190
	s_nop 1
	v_addc_co_u32_e32 v193, vcc, 0, v191, vcc
	v_add_co_u32_e32 v194, vcc, s80, v190
	s_movk_i32 s8, 0x3000
	s_nop 0
	v_addc_co_u32_e32 v195, vcc, 0, v191, vcc
	v_add_co_u32_e32 v196, vcc, s8, v190
	s_nop 1
	v_addc_co_u32_e32 v197, vcc, 0, v191, vcc
	global_load_dword v246, v[190:191], off
	global_load_dword v247, v[192:193], off
	global_load_dword v248, v[194:195], off
	global_load_dword v249, v[196:197], off
	global_load_dword v250, v[190:191], off offset:64
	global_load_dword v251, v[192:193], off offset:64
	global_load_dword v252, v[194:195], off offset:64
	global_load_dword v253, v[196:197], off offset:64
	s_waitcnt vmcnt(8)
	v_cvt_pk_bf16_f32 v102, v102, v103
	v_cvt_pk_bf16_f32 v103, v104, v105
	v_cvt_pk_bf16_f32 v104, v118, v119
	v_cvt_pk_bf16_f32 v105, v120, v121
	v_cvt_pk_bf16_f32 v118, v238, v239
	v_cvt_pk_bf16_f32 v119, v240, v241
	v_cvt_pk_bf16_f32 v120, v184, v185
	v_cvt_pk_bf16_f32 v121, v186, v187
	global_load_dword v238, v[190:191], off offset:128
	global_load_dword v239, v[192:193], off offset:128
	global_load_dword v240, v[194:195], off offset:128
	global_load_dword v241, v[196:197], off offset:128
	global_load_dword v242, v[190:191], off offset:192
	global_load_dword v243, v[192:193], off offset:192
	global_load_dword v244, v[194:195], off offset:192
	global_load_dword v245, v[196:197], off offset:192
	s_waitcnt vmcnt(8)
	v_cvt_pk_bf16_f32 v184, v246, v247
	v_cvt_pk_bf16_f32 v185, v248, v249
	v_cvt_pk_bf16_f32 v186, v250, v251
	v_cvt_pk_bf16_f32 v187, v252, v253
	s_waitcnt vmcnt(0)
	v_cvt_pk_bf16_f32 v188, v238, v239
	v_cvt_pk_bf16_f32 v189, v240, v241
	v_cvt_pk_bf16_f32 v190, v242, v243
	v_cvt_pk_bf16_f32 v191, v244, v245
